# norm0 gate-logit projection: packed f32 FMAs, 8-deep weight read ring, transpose-reduce (permlane swaps + DPP) instead of 96 bpermute hops
# speedup vs baseline: 1.0152x; 1.0090x over previous
; DI unsigned pack2(float a, float b) { f32v2_t v = {a, b}; bf16v2_t r = __builtin_convertvector(v, bf16v2_t); return __builtin_bit_cast(unsigned, r); }
; DI void norm_phase(const Params& p, int l, int mode, int B, int G, char* smem) {
;     ...
;   for (int row = B * 8 + wid; row < MT; row += G * 8) {
;     float* X = p.out + (size_t)row * 1024;
;     const float* Xr = (mode == 0 && l == 0 && row < MP) ? p.in[0] + (size_t)row * 1024 : X;
;     float4 v[4];
;     float ss = 0.f;
; #pragma unroll
;     for (int i = 0; i < 4; ++i) { { const f32x4 t4 = __builtin_nontemporal_load((const f32x4*)(Xr + i * 256 + lane * 4)); v[i] = float4{t4[0], t4[1], t4[2], t4[3]}; } ss += v[i].x * v[i].x + v[i].y * v[i].y + v[i].z * v[i].z + v[i].w * v[i].w; }
;     ss = wave_sum(ss);
;     const float rs = rsqrtf(ss * (1.f / 1024.f) + EPS);
;     u16* XN = (u16*)(p.ws + O_XN) + (size_t)row * LDK;
; #pragma unroll
;     for (int i = 0; i < 4; ++i) {
;       v[i] = float4{v[i].x * rs * g[i].x, v[i].y * rs * g[i].y, v[i].z * rs * g[i].z, v[i].w * rs * g[i].w};
;       if (mode == 2) *(float4*)(X + i * 256 + lane * 4) = v[i];
;       else *(uint2*)(XN + i * 256 + lane * 4) = uint2{pack2(v[i].x, v[i].y), pack2(v[i].z, v[i].w)};
;     }
;     if (mode == 0) {
;       float ga[16];
; #pragma unroll
;       for (int r = 0; r < 16; ++r) ga[r] = 0.f;
; #pragma unroll
;       for (int i = 0; i < 4; ++i) {
;         const float xv[4] = {v[i].x, v[i].y, v[i].z, v[i].w};
; #pragma unroll
;         for (int e = 0; e < 4; ++e) {
;           asm volatile("" ::: "memory");
; #pragma unroll
;           for (int q = 0; q < 4; ++q) {
;             const float4 w = ((const float4*)wga)[((i * 4 + e) * 4 + q) * 64 + lane];
;             ga[q * 4 + 0] += xv[e] * w.x; ga[q * 4 + 1] += xv[e] * w.y; ga[q * 4 + 2] += xv[e] * w.z; ga[q * 4 + 3] += xv[e] * w.w;
;           }
;         }
;       }
.LBB0_79:
	s_waitcnt vmcnt(0)
	v_mov_b32_e32 v26, v104
	v_mov_b32_e32 v27, v105
	v_mov_b32_e32 v28, v106
	v_mov_b32_e32 v29, v107
	v_mov_b32_e32 v30, v108
	v_mov_b32_e32 v31, v109
	v_mov_b32_e32 v32, v110
	v_mov_b32_e32 v33, v111
	v_mov_b32_e32 v34, v112
	v_mov_b32_e32 v35, v113
	v_mov_b32_e32 v36, v114
	v_mov_b32_e32 v37, v115
	v_mov_b32_e32 v46, v116
	v_mov_b32_e32 v47, v117
	v_mov_b32_e32 v48, v118
	v_mov_b32_e32 v49, v119
	v_readlane_b32 s20, v254, 31
	v_readlane_b32 s10, v254, 33
	v_readlane_b32 s11, v254, 34
	v_add_u32_e32 v120, s20, v0
	s_nop 0
	v_lshl_add_u64 v[122:123], v[22:23], 0, s[10:11]
	v_cmp_ge_i32_e64 s[34:35], s24, v120
	s_nop 1
	v_cndmask_b32_e64 v120, v0, v120, s[34:35]
	v_cndmask_b32_e64 v122, v22, v122, s[34:35]
	v_cndmask_b32_e64 v123, v23, v123, s[34:35]
	v_cmp_gt_i32_e64 s[72:73], s28, v120
	v_readlane_b32 s10, v253, 63
	v_readlane_b32 s11, v254, 0
	s_and_b64 s[72:73], s[6:7], s[72:73]
	v_mov_b32_e32 v121, s93
	v_mov_b32_e32 v124, s11
	v_cndmask_b32_e64 v125, v121, v124, s[72:73]
	v_mov_b32_e32 v121, s92
	v_mov_b32_e32 v124, s10
	v_cndmask_b32_e64 v124, v121, v124, s[72:73]
	v_lshl_add_u64 v[124:125], v[124:125], 0, v[122:123]
	global_load_dwordx4 v[104:107], v[124:125], off nt
	global_load_dwordx4 v[108:111], v[124:125], off offset:1024 nt
	global_load_dwordx4 v[112:115], v[124:125], off offset:2048 nt
	global_load_dwordx4 v[116:119], v[124:125], off offset:3072 nt
	s_waitcnt lgkmcnt(2)
	s_mov_b32 s10, 0xa544000
	v_mov_b32_e32 v50, v27
	v_mov_b32_e32 v51, v31
	v_mov_b32_e32 v38, v26
	v_mov_b32_e32 v39, v30
	v_mov_b32_e32 v58, v35
	v_mov_b32_e32 v59, v47
	v_pk_mul_f32 v[50:51], v[50:51], v[50:51]
	v_mov_b32_e32 v52, v28
	v_mov_b32_e32 v53, v32
	v_mov_b32_e32 v56, v34
	v_mov_b32_e32 v57, v46
	v_pk_mul_f32 v[58:59], v[58:59], v[58:59]
	v_pk_fma_f32 v[38:39], v[38:39], v[38:39], v[50:51]
	v_mov_b32_e32 v54, v29
	v_mov_b32_e32 v55, v33
	s_waitcnt lgkmcnt(1)
	v_mov_b32_e32 v60, v36
	v_mov_b32_e32 v61, v48
	v_pk_fma_f32 v[50:51], v[56:57], v[56:57], v[58:59]
	v_pk_fma_f32 v[38:39], v[52:53], v[52:53], v[38:39]
	s_waitcnt lgkmcnt(0)
	v_mov_b32_e32 v62, v37
	v_mov_b32_e32 v63, v49
	v_pk_fma_f32 v[50:51], v[60:61], v[60:61], v[50:51]
	v_pk_fma_f32 v[38:39], v[54:55], v[54:55], v[38:39]
	v_pk_fma_f32 v[50:51], v[62:63], v[62:63], v[50:51]
	v_add_f32_e32 v1, v38, v39
	v_add_f32_e32 v1, v1, v50
	v_add_f32_e32 v1, v1, v51
	ds_bpermute_b32 v38, v2, v1
	s_waitcnt lgkmcnt(0)
	v_add_f32_e32 v1, v1, v38
	ds_bpermute_b32 v38, v40, v1
	s_waitcnt lgkmcnt(0)
	v_add_f32_e32 v1, v1, v38
	ds_bpermute_b32 v38, v41, v1
	s_waitcnt lgkmcnt(0)
	v_add_f32_e32 v1, v1, v38
	ds_bpermute_b32 v38, v42, v1
	s_waitcnt lgkmcnt(0)
	v_add_f32_e32 v1, v1, v38
	ds_bpermute_b32 v38, v43, v1
	s_waitcnt lgkmcnt(0)
	v_add_f32_e32 v1, v1, v38
	ds_bpermute_b32 v50, v44, v1
	v_lshl_add_u64 v[38:39], s[94:95], 0, v[20:21]
	s_waitcnt lgkmcnt(0)
	v_add_f32_e32 v1, v1, v50
	v_fmamk_f32 v1, v1, 0x3a800000, v186
	v_mul_f32_e32 v50, 0x4b800000, v1
	v_cmp_gt_f32_e64 s[72:73], s1, v1
	s_nop 1
	v_cndmask_b32_e64 v1, v1, v50, s[72:73]
	v_rsq_f32_e32 v1, v1
	v_add_co_u32_e64 v50, s[74:75], s10, v38
	v_mul_f32_e32 v38, 0x45800000, v1
	v_cndmask_b32_e64 v38, v1, v38, s[72:73]
	v_pk_mul_f32 v[26:27], v[26:27], v[38:39] op_sel_hi:[1,0]
	v_pk_mul_f32 v[28:29], v[28:29], v[38:39] op_sel_hi:[1,0]
	v_addc_co_u32_e64 v51, s[74:75], 0, v39, s[74:75]
	v_pk_mul_f32 v[30:31], v[30:31], v[38:39] op_sel_hi:[1,0]
	v_pk_mul_f32 v[32:33], v[32:33], v[38:39] op_sel_hi:[1,0]
	v_pk_mul_f32 v[52:53], v[34:35], v[38:39] op_sel_hi:[1,0]
	v_pk_mul_f32 v[54:55], v[36:37], v[38:39] op_sel_hi:[1,0]
	v_pk_mul_f32 v[46:47], v[46:47], v[38:39] op_sel_hi:[1,0]
	v_pk_mul_f32 v[48:49], v[48:49], v[38:39] op_sel_hi:[1,0]
	v_pk_mul_f32 v[102:103], v[4:5], v[26:27]
	v_pk_mul_f32 v[38:39], v[6:7], v[28:29]
	v_pk_mul_f32 v[36:37], v[8:9], v[30:31]
	v_pk_mul_f32 v[34:35], v[10:11], v[32:33]
	v_pk_mul_f32 v[32:33], v[12:13], v[52:53]
	v_pk_mul_f32 v[30:31], v[14:15], v[54:55]
	v_pk_mul_f32 v[28:29], v[16:17], v[46:47]
	v_pk_mul_f32 v[26:27], v[18:19], v[48:49]
	v_cvt_pk_bf16_f32 v46, v102, v103
	v_cvt_pk_bf16_f32 v47, v38, v39
	v_cvt_pk_bf16_f32 v48, v36, v37
	v_cvt_pk_bf16_f32 v49, v34, v35
	v_cvt_pk_bf16_f32 v52, v32, v33
	v_cvt_pk_bf16_f32 v53, v30, v31
	v_cvt_pk_bf16_f32 v54, v28, v29
	v_cvt_pk_bf16_f32 v55, v26, v27
	global_store_dwordx2 v[50:51], v[46:47], off offset:256
	global_store_dwordx2 v[50:51], v[48:49], off offset:768
	global_store_dwordx2 v[50:51], v[52:53], off offset:1280
	global_store_dwordx2 v[50:51], v[54:55], off offset:1792
	ds_read_b128 v[128:131], v45
	ds_read_b128 v[132:135], v45 offset:1024
	ds_read_b128 v[136:139], v45 offset:2048
	ds_read_b128 v[140:143], v45 offset:3072
	ds_read_b128 v[144:147], v45 offset:4096
	ds_read_b128 v[148:151], v45 offset:5120
	ds_read_b128 v[152:155], v45 offset:6144
	ds_read_b128 v[156:159], v45 offset:7168
	s_waitcnt lgkmcnt(7)
	v_pk_mul_f32 v[214:215], v[102:103], v[128:129] op_sel:[0,0] op_sel_hi:[0,1]
	v_pk_mul_f32 v[216:217], v[102:103], v[130:131] op_sel:[0,0] op_sel_hi:[0,1]
	ds_read_b128 v[128:131], v45 offset:8192
	s_waitcnt lgkmcnt(7)
	v_pk_mul_f32 v[218:219], v[102:103], v[132:133] op_sel:[0,0] op_sel_hi:[0,1]
	v_pk_mul_f32 v[220:221], v[102:103], v[134:135] op_sel:[0,0] op_sel_hi:[0,1]
	ds_read_b128 v[132:135], v45 offset:9216
	s_waitcnt lgkmcnt(7)
	v_pk_mul_f32 v[222:223], v[102:103], v[136:137] op_sel:[0,0] op_sel_hi:[0,1]
	v_pk_mul_f32 v[224:225], v[102:103], v[138:139] op_sel:[0,0] op_sel_hi:[0,1]
	ds_read_b128 v[136:139], v45 offset:10240
	s_waitcnt lgkmcnt(7)
; DI void norm_phase(const Params& p, int l, int mode, int B, int G, char* smem) {
;     ...
;       float ga[16];
; #pragma unroll
;       for (int r = 0; r < 16; ++r) ga[r] = 0.f;
; #pragma unroll
;       for (int i = 0; i < 4; ++i) {
;         const float xv[4] = {v[i].x, v[i].y, v[i].z, v[i].w};
; #pragma unroll
;         for (int e = 0; e < 4; ++e) {
;           asm volatile("" ::: "memory");
; #pragma unroll
;           for (int q = 0; q < 4; ++q) {
;             const float4 w = ((const float4*)wga)[((i * 4 + e) * 4 + q) * 64 + lane];
;             ga[q * 4 + 0] += xv[e] * w.x; ga[q * 4 + 1] += xv[e] * w.y; ga[q * 4 + 2] += xv[e] * w.z; ga[q * 4 + 3] += xv[e] * w.w;
;           }
;         }
;       }
	v_pk_mul_f32 v[226:227], v[102:103], v[140:141] op_sel:[0,0] op_sel_hi:[0,1]
	v_pk_mul_f32 v[228:229], v[102:103], v[142:143] op_sel:[0,0] op_sel_hi:[0,1]
	ds_read_b128 v[140:143], v45 offset:11264
	s_waitcnt lgkmcnt(7)
	v_pk_fma_f32 v[214:215], v[102:103], v[144:145], v[214:215] op_sel:[1,0,0] op_sel_hi:[1,1,1]
	v_pk_fma_f32 v[216:217], v[102:103], v[146:147], v[216:217] op_sel:[1,0,0] op_sel_hi:[1,1,1]
	ds_read_b128 v[144:147], v45 offset:12288
	s_waitcnt lgkmcnt(7)
	v_pk_fma_f32 v[218:219], v[102:103], v[148:149], v[218:219] op_sel:[1,0,0] op_sel_hi:[1,1,1]
	v_pk_fma_f32 v[220:221], v[102:103], v[150:151], v[220:221] op_sel:[1,0,0] op_sel_hi:[1,1,1]
	ds_read_b128 v[148:151], v45 offset:13312
	s_waitcnt lgkmcnt(7)
	v_pk_fma_f32 v[222:223], v[102:103], v[152:153], v[222:223] op_sel:[1,0,0] op_sel_hi:[1,1,1]
	v_pk_fma_f32 v[224:225], v[102:103], v[154:155], v[224:225] op_sel:[1,0,0] op_sel_hi:[1,1,1]
	ds_read_b128 v[152:155], v45 offset:14336
	s_waitcnt lgkmcnt(7)
	v_pk_fma_f32 v[226:227], v[102:103], v[156:157], v[226:227] op_sel:[1,0,0] op_sel_hi:[1,1,1]
	v_pk_fma_f32 v[228:229], v[102:103], v[158:159], v[228:229] op_sel:[1,0,0] op_sel_hi:[1,1,1]
	ds_read_b128 v[156:159], v45 offset:15360
	s_waitcnt lgkmcnt(7)
	v_pk_fma_f32 v[214:215], v[38:39], v[128:129], v[214:215] op_sel:[0,0,0] op_sel_hi:[0,1,1]
	v_pk_fma_f32 v[216:217], v[38:39], v[130:131], v[216:217] op_sel:[0,0,0] op_sel_hi:[0,1,1]
	ds_read_b128 v[128:131], v45 offset:16384
	s_waitcnt lgkmcnt(7)
	v_pk_fma_f32 v[218:219], v[38:39], v[132:133], v[218:219] op_sel:[0,0,0] op_sel_hi:[0,1,1]
	v_pk_fma_f32 v[220:221], v[38:39], v[134:135], v[220:221] op_sel:[0,0,0] op_sel_hi:[0,1,1]
	ds_read_b128 v[132:135], v45 offset:17408
	s_waitcnt lgkmcnt(7)
	v_pk_fma_f32 v[222:223], v[38:39], v[136:137], v[222:223] op_sel:[0,0,0] op_sel_hi:[0,1,1]
	v_pk_fma_f32 v[224:225], v[38:39], v[138:139], v[224:225] op_sel:[0,0,0] op_sel_hi:[0,1,1]
	ds_read_b128 v[136:139], v45 offset:18432
	s_waitcnt lgkmcnt(7)
	v_pk_fma_f32 v[226:227], v[38:39], v[140:141], v[226:227] op_sel:[0,0,0] op_sel_hi:[0,1,1]
	v_pk_fma_f32 v[228:229], v[38:39], v[142:143], v[228:229] op_sel:[0,0,0] op_sel_hi:[0,1,1]
	ds_read_b128 v[140:143], v45 offset:19456
	s_waitcnt lgkmcnt(7)
	v_pk_fma_f32 v[214:215], v[38:39], v[144:145], v[214:215] op_sel:[1,0,0] op_sel_hi:[1,1,1]
	v_pk_fma_f32 v[216:217], v[38:39], v[146:147], v[216:217] op_sel:[1,0,0] op_sel_hi:[1,1,1]
	ds_read_b128 v[144:147], v45 offset:20480
	s_waitcnt lgkmcnt(7)
	v_pk_fma_f32 v[218:219], v[38:39], v[148:149], v[218:219] op_sel:[1,0,0] op_sel_hi:[1,1,1]
	v_pk_fma_f32 v[220:221], v[38:39], v[150:151], v[220:221] op_sel:[1,0,0] op_sel_hi:[1,1,1]
	ds_read_b128 v[148:151], v45 offset:21504
	s_waitcnt lgkmcnt(7)
	v_pk_fma_f32 v[222:223], v[38:39], v[152:153], v[222:223] op_sel:[1,0,0] op_sel_hi:[1,1,1]
	v_pk_fma_f32 v[224:225], v[38:39], v[154:155], v[224:225] op_sel:[1,0,0] op_sel_hi:[1,1,1]
	ds_read_b128 v[152:155], v45 offset:22528
	s_waitcnt lgkmcnt(7)
	v_pk_fma_f32 v[226:227], v[38:39], v[156:157], v[226:227] op_sel:[1,0,0] op_sel_hi:[1,1,1]
	v_pk_fma_f32 v[228:229], v[38:39], v[158:159], v[228:229] op_sel:[1,0,0] op_sel_hi:[1,1,1]
	ds_read_b128 v[156:159], v45 offset:23552
	s_waitcnt lgkmcnt(7)
	v_pk_fma_f32 v[214:215], v[36:37], v[128:129], v[214:215] op_sel:[0,0,0] op_sel_hi:[0,1,1]
	v_pk_fma_f32 v[216:217], v[36:37], v[130:131], v[216:217] op_sel:[0,0,0] op_sel_hi:[0,1,1]
	ds_read_b128 v[128:131], v45 offset:24576
	s_waitcnt lgkmcnt(7)
	v_pk_fma_f32 v[218:219], v[36:37], v[132:133], v[218:219] op_sel:[0,0,0] op_sel_hi:[0,1,1]
	v_pk_fma_f32 v[220:221], v[36:37], v[134:135], v[220:221] op_sel:[0,0,0] op_sel_hi:[0,1,1]
	ds_read_b128 v[132:135], v45 offset:25600
	s_waitcnt lgkmcnt(7)
	v_pk_fma_f32 v[222:223], v[36:37], v[136:137], v[222:223] op_sel:[0,0,0] op_sel_hi:[0,1,1]
	v_pk_fma_f32 v[224:225], v[36:37], v[138:139], v[224:225] op_sel:[0,0,0] op_sel_hi:[0,1,1]
	ds_read_b128 v[136:139], v45 offset:26624
	s_waitcnt lgkmcnt(7)
	v_pk_fma_f32 v[226:227], v[36:37], v[140:141], v[226:227] op_sel:[0,0,0] op_sel_hi:[0,1,1]
	v_pk_fma_f32 v[228:229], v[36:37], v[142:143], v[228:229] op_sel:[0,0,0] op_sel_hi:[0,1,1]
	ds_read_b128 v[140:143], v45 offset:27648
	s_waitcnt lgkmcnt(7)
	v_pk_fma_f32 v[214:215], v[36:37], v[144:145], v[214:215] op_sel:[1,0,0] op_sel_hi:[1,1,1]
	v_pk_fma_f32 v[216:217], v[36:37], v[146:147], v[216:217] op_sel:[1,0,0] op_sel_hi:[1,1,1]
	ds_read_b128 v[144:147], v45 offset:28672
	s_waitcnt lgkmcnt(7)
	v_pk_fma_f32 v[218:219], v[36:37], v[148:149], v[218:219] op_sel:[1,0,0] op_sel_hi:[1,1,1]
	v_pk_fma_f32 v[220:221], v[36:37], v[150:151], v[220:221] op_sel:[1,0,0] op_sel_hi:[1,1,1]
	ds_read_b128 v[148:151], v45 offset:29696
	s_waitcnt lgkmcnt(7)
	v_pk_fma_f32 v[222:223], v[36:37], v[152:153], v[222:223] op_sel:[1,0,0] op_sel_hi:[1,1,1]
	v_pk_fma_f32 v[224:225], v[36:37], v[154:155], v[224:225] op_sel:[1,0,0] op_sel_hi:[1,1,1]
	ds_read_b128 v[152:155], v45 offset:30720
	s_waitcnt lgkmcnt(7)
	v_pk_fma_f32 v[226:227], v[36:37], v[156:157], v[226:227] op_sel:[1,0,0] op_sel_hi:[1,1,1]
	v_pk_fma_f32 v[228:229], v[36:37], v[158:159], v[228:229] op_sel:[1,0,0] op_sel_hi:[1,1,1]
	ds_read_b128 v[156:159], v45 offset:31744
	s_waitcnt lgkmcnt(7)
	v_pk_fma_f32 v[214:215], v[34:35], v[128:129], v[214:215] op_sel:[0,0,0] op_sel_hi:[0,1,1]
	v_pk_fma_f32 v[216:217], v[34:35], v[130:131], v[216:217] op_sel:[0,0,0] op_sel_hi:[0,1,1]
	ds_read_b128 v[128:131], v45 offset:32768
	s_waitcnt lgkmcnt(7)
	v_pk_fma_f32 v[218:219], v[34:35], v[132:133], v[218:219] op_sel:[0,0,0] op_sel_hi:[0,1,1]
	v_pk_fma_f32 v[220:221], v[34:35], v[134:135], v[220:221] op_sel:[0,0,0] op_sel_hi:[0,1,1]
	ds_read_b128 v[132:135], v45 offset:33792
	s_waitcnt lgkmcnt(7)
; DI void norm_phase(const Params& p, int l, int mode, int B, int G, char* smem) {
;     ...
;       float ga[16];
; #pragma unroll
;       for (int r = 0; r < 16; ++r) ga[r] = 0.f;
; #pragma unroll
;       for (int i = 0; i < 4; ++i) {
;         const float xv[4] = {v[i].x, v[i].y, v[i].z, v[i].w};
; #pragma unroll
;         for (int e = 0; e < 4; ++e) {
;           asm volatile("" ::: "memory");
; #pragma unroll
;           for (int q = 0; q < 4; ++q) {
;             const float4 w = ((const float4*)wga)[((i * 4 + e) * 4 + q) * 64 + lane];
;             ga[q * 4 + 0] += xv[e] * w.x; ga[q * 4 + 1] += xv[e] * w.y; ga[q * 4 + 2] += xv[e] * w.z; ga[q * 4 + 3] += xv[e] * w.w;
;           }
;         }
;       }
	v_pk_fma_f32 v[222:223], v[34:35], v[136:137], v[222:223] op_sel:[0,0,0] op_sel_hi:[0,1,1]
	v_pk_fma_f32 v[224:225], v[34:35], v[138:139], v[224:225] op_sel:[0,0,0] op_sel_hi:[0,1,1]
	ds_read_b128 v[136:139], v45 offset:34816
	s_waitcnt lgkmcnt(7)
	v_pk_fma_f32 v[226:227], v[34:35], v[140:141], v[226:227] op_sel:[0,0,0] op_sel_hi:[0,1,1]
	v_pk_fma_f32 v[228:229], v[34:35], v[142:143], v[228:229] op_sel:[0,0,0] op_sel_hi:[0,1,1]
	ds_read_b128 v[140:143], v45 offset:35840
	s_waitcnt lgkmcnt(7)
	v_pk_fma_f32 v[214:215], v[34:35], v[144:145], v[214:215] op_sel:[1,0,0] op_sel_hi:[1,1,1]
	v_pk_fma_f32 v[216:217], v[34:35], v[146:147], v[216:217] op_sel:[1,0,0] op_sel_hi:[1,1,1]
	ds_read_b128 v[144:147], v45 offset:36864
	s_waitcnt lgkmcnt(7)
	v_pk_fma_f32 v[218:219], v[34:35], v[148:149], v[218:219] op_sel:[1,0,0] op_sel_hi:[1,1,1]
	v_pk_fma_f32 v[220:221], v[34:35], v[150:151], v[220:221] op_sel:[1,0,0] op_sel_hi:[1,1,1]
	ds_read_b128 v[148:151], v45 offset:37888
	s_waitcnt lgkmcnt(7)
	v_pk_fma_f32 v[222:223], v[34:35], v[152:153], v[222:223] op_sel:[1,0,0] op_sel_hi:[1,1,1]
	v_pk_fma_f32 v[224:225], v[34:35], v[154:155], v[224:225] op_sel:[1,0,0] op_sel_hi:[1,1,1]
	ds_read_b128 v[152:155], v45 offset:38912
	s_waitcnt lgkmcnt(7)
	v_pk_fma_f32 v[226:227], v[34:35], v[156:157], v[226:227] op_sel:[1,0,0] op_sel_hi:[1,1,1]
	v_pk_fma_f32 v[228:229], v[34:35], v[158:159], v[228:229] op_sel:[1,0,0] op_sel_hi:[1,1,1]
	ds_read_b128 v[156:159], v45 offset:39936
	s_waitcnt lgkmcnt(7)
	v_pk_fma_f32 v[214:215], v[32:33], v[128:129], v[214:215] op_sel:[0,0,0] op_sel_hi:[0,1,1]
	v_pk_fma_f32 v[216:217], v[32:33], v[130:131], v[216:217] op_sel:[0,0,0] op_sel_hi:[0,1,1]
	ds_read_b128 v[128:131], v45 offset:40960
	s_waitcnt lgkmcnt(7)
	v_pk_fma_f32 v[218:219], v[32:33], v[132:133], v[218:219] op_sel:[0,0,0] op_sel_hi:[0,1,1]
	v_pk_fma_f32 v[220:221], v[32:33], v[134:135], v[220:221] op_sel:[0,0,0] op_sel_hi:[0,1,1]
	ds_read_b128 v[132:135], v45 offset:41984
	s_waitcnt lgkmcnt(7)
	v_pk_fma_f32 v[222:223], v[32:33], v[136:137], v[222:223] op_sel:[0,0,0] op_sel_hi:[0,1,1]
	v_pk_fma_f32 v[224:225], v[32:33], v[138:139], v[224:225] op_sel:[0,0,0] op_sel_hi:[0,1,1]
	ds_read_b128 v[136:139], v45 offset:43008
	s_waitcnt lgkmcnt(7)
	v_pk_fma_f32 v[226:227], v[32:33], v[140:141], v[226:227] op_sel:[0,0,0] op_sel_hi:[0,1,1]
	v_pk_fma_f32 v[228:229], v[32:33], v[142:143], v[228:229] op_sel:[0,0,0] op_sel_hi:[0,1,1]
	ds_read_b128 v[140:143], v45 offset:44032
	s_waitcnt lgkmcnt(7)
	v_pk_fma_f32 v[214:215], v[32:33], v[144:145], v[214:215] op_sel:[1,0,0] op_sel_hi:[1,1,1]
	v_pk_fma_f32 v[216:217], v[32:33], v[146:147], v[216:217] op_sel:[1,0,0] op_sel_hi:[1,1,1]
	ds_read_b128 v[144:147], v45 offset:45056
	s_waitcnt lgkmcnt(7)
	v_pk_fma_f32 v[218:219], v[32:33], v[148:149], v[218:219] op_sel:[1,0,0] op_sel_hi:[1,1,1]
	v_pk_fma_f32 v[220:221], v[32:33], v[150:151], v[220:221] op_sel:[1,0,0] op_sel_hi:[1,1,1]
	ds_read_b128 v[148:151], v45 offset:46080
	s_waitcnt lgkmcnt(7)
	v_pk_fma_f32 v[222:223], v[32:33], v[152:153], v[222:223] op_sel:[1,0,0] op_sel_hi:[1,1,1]
	v_pk_fma_f32 v[224:225], v[32:33], v[154:155], v[224:225] op_sel:[1,0,0] op_sel_hi:[1,1,1]
	ds_read_b128 v[152:155], v45 offset:47104
	s_waitcnt lgkmcnt(7)
	v_pk_fma_f32 v[226:227], v[32:33], v[156:157], v[226:227] op_sel:[1,0,0] op_sel_hi:[1,1,1]
	v_pk_fma_f32 v[228:229], v[32:33], v[158:159], v[228:229] op_sel:[1,0,0] op_sel_hi:[1,1,1]
	ds_read_b128 v[156:159], v45 offset:48128
	s_waitcnt lgkmcnt(7)
	v_pk_fma_f32 v[214:215], v[30:31], v[128:129], v[214:215] op_sel:[0,0,0] op_sel_hi:[0,1,1]
	v_pk_fma_f32 v[216:217], v[30:31], v[130:131], v[216:217] op_sel:[0,0,0] op_sel_hi:[0,1,1]
	ds_read_b128 v[128:131], v45 offset:49152
	s_waitcnt lgkmcnt(7)
	v_pk_fma_f32 v[218:219], v[30:31], v[132:133], v[218:219] op_sel:[0,0,0] op_sel_hi:[0,1,1]
	v_pk_fma_f32 v[220:221], v[30:31], v[134:135], v[220:221] op_sel:[0,0,0] op_sel_hi:[0,1,1]
	ds_read_b128 v[132:135], v45 offset:50176
	s_waitcnt lgkmcnt(7)
	v_pk_fma_f32 v[222:223], v[30:31], v[136:137], v[222:223] op_sel:[0,0,0] op_sel_hi:[0,1,1]
	v_pk_fma_f32 v[224:225], v[30:31], v[138:139], v[224:225] op_sel:[0,0,0] op_sel_hi:[0,1,1]
	ds_read_b128 v[136:139], v45 offset:51200
	s_waitcnt lgkmcnt(7)
	v_pk_fma_f32 v[226:227], v[30:31], v[140:141], v[226:227] op_sel:[0,0,0] op_sel_hi:[0,1,1]
	v_pk_fma_f32 v[228:229], v[30:31], v[142:143], v[228:229] op_sel:[0,0,0] op_sel_hi:[0,1,1]
	ds_read_b128 v[140:143], v45 offset:52224
	s_waitcnt lgkmcnt(7)
	v_pk_fma_f32 v[214:215], v[30:31], v[144:145], v[214:215] op_sel:[1,0,0] op_sel_hi:[1,1,1]
	v_pk_fma_f32 v[216:217], v[30:31], v[146:147], v[216:217] op_sel:[1,0,0] op_sel_hi:[1,1,1]
	ds_read_b128 v[144:147], v45 offset:53248
	s_waitcnt lgkmcnt(7)
	v_pk_fma_f32 v[218:219], v[30:31], v[148:149], v[218:219] op_sel:[1,0,0] op_sel_hi:[1,1,1]
	v_pk_fma_f32 v[220:221], v[30:31], v[150:151], v[220:221] op_sel:[1,0,0] op_sel_hi:[1,1,1]
	ds_read_b128 v[148:151], v45 offset:54272
	s_waitcnt lgkmcnt(7)
	v_pk_fma_f32 v[222:223], v[30:31], v[152:153], v[222:223] op_sel:[1,0,0] op_sel_hi:[1,1,1]
	v_pk_fma_f32 v[224:225], v[30:31], v[154:155], v[224:225] op_sel:[1,0,0] op_sel_hi:[1,1,1]
	ds_read_b128 v[152:155], v45 offset:55296
	s_waitcnt lgkmcnt(7)
	v_pk_fma_f32 v[226:227], v[30:31], v[156:157], v[226:227] op_sel:[1,0,0] op_sel_hi:[1,1,1]
	v_pk_fma_f32 v[228:229], v[30:31], v[158:159], v[228:229] op_sel:[1,0,0] op_sel_hi:[1,1,1]
	ds_read_b128 v[156:159], v45 offset:56320
	s_waitcnt lgkmcnt(7)
; DI void norm_phase(const Params& p, int l, int mode, int B, int G, char* smem) {
;     ...
;       float ga[16];
; #pragma unroll
;       for (int r = 0; r < 16; ++r) ga[r] = 0.f;
; #pragma unroll
;       for (int i = 0; i < 4; ++i) {
;         const float xv[4] = {v[i].x, v[i].y, v[i].z, v[i].w};
; #pragma unroll
;         for (int e = 0; e < 4; ++e) {
;           asm volatile("" ::: "memory");
; #pragma unroll
;           for (int q = 0; q < 4; ++q) {
;             const float4 w = ((const float4*)wga)[((i * 4 + e) * 4 + q) * 64 + lane];
;             ga[q * 4 + 0] += xv[e] * w.x; ga[q * 4 + 1] += xv[e] * w.y; ga[q * 4 + 2] += xv[e] * w.z; ga[q * 4 + 3] += xv[e] * w.w;
;           }
;         }
;       }
;       float mine = 0.f;
; #pragma unroll
;       for (int r = 0; r < 16; ++r) { const float s = wave_sum(ga[r]); if (lane == r) mine = s; }
;       if (lane < 16) ((float*)(p.ws + O_GA))[(size_t)row * 16 + lane] = mine;
	v_pk_fma_f32 v[214:215], v[28:29], v[128:129], v[214:215] op_sel:[0,0,0] op_sel_hi:[0,1,1]
	v_pk_fma_f32 v[216:217], v[28:29], v[130:131], v[216:217] op_sel:[0,0,0] op_sel_hi:[0,1,1]
	ds_read_b128 v[128:131], v45 offset:57344
	s_waitcnt lgkmcnt(7)
	v_pk_fma_f32 v[218:219], v[28:29], v[132:133], v[218:219] op_sel:[0,0,0] op_sel_hi:[0,1,1]
	v_pk_fma_f32 v[220:221], v[28:29], v[134:135], v[220:221] op_sel:[0,0,0] op_sel_hi:[0,1,1]
	ds_read_b128 v[132:135], v45 offset:58368
	s_waitcnt lgkmcnt(7)
	v_pk_fma_f32 v[222:223], v[28:29], v[136:137], v[222:223] op_sel:[0,0,0] op_sel_hi:[0,1,1]
	v_pk_fma_f32 v[224:225], v[28:29], v[138:139], v[224:225] op_sel:[0,0,0] op_sel_hi:[0,1,1]
	ds_read_b128 v[136:139], v45 offset:59392
	s_waitcnt lgkmcnt(7)
	v_pk_fma_f32 v[226:227], v[28:29], v[140:141], v[226:227] op_sel:[0,0,0] op_sel_hi:[0,1,1]
	v_pk_fma_f32 v[228:229], v[28:29], v[142:143], v[228:229] op_sel:[0,0,0] op_sel_hi:[0,1,1]
	ds_read_b128 v[140:143], v45 offset:60416
	s_waitcnt lgkmcnt(7)
	v_pk_fma_f32 v[214:215], v[28:29], v[144:145], v[214:215] op_sel:[1,0,0] op_sel_hi:[1,1,1]
	v_pk_fma_f32 v[216:217], v[28:29], v[146:147], v[216:217] op_sel:[1,0,0] op_sel_hi:[1,1,1]
	ds_read_b128 v[144:147], v45 offset:61440
	s_waitcnt lgkmcnt(7)
	v_pk_fma_f32 v[218:219], v[28:29], v[148:149], v[218:219] op_sel:[1,0,0] op_sel_hi:[1,1,1]
	v_pk_fma_f32 v[220:221], v[28:29], v[150:151], v[220:221] op_sel:[1,0,0] op_sel_hi:[1,1,1]
	ds_read_b128 v[148:151], v45 offset:62464
	s_waitcnt lgkmcnt(7)
	v_pk_fma_f32 v[222:223], v[28:29], v[152:153], v[222:223] op_sel:[1,0,0] op_sel_hi:[1,1,1]
	v_pk_fma_f32 v[224:225], v[28:29], v[154:155], v[224:225] op_sel:[1,0,0] op_sel_hi:[1,1,1]
	ds_read_b128 v[152:155], v45 offset:63488
	s_waitcnt lgkmcnt(7)
	v_pk_fma_f32 v[226:227], v[28:29], v[156:157], v[226:227] op_sel:[1,0,0] op_sel_hi:[1,1,1]
	v_pk_fma_f32 v[228:229], v[28:29], v[158:159], v[228:229] op_sel:[1,0,0] op_sel_hi:[1,1,1]
	ds_read_b128 v[156:159], v45 offset:64512
	s_waitcnt lgkmcnt(7)
	v_pk_fma_f32 v[214:215], v[26:27], v[128:129], v[214:215] op_sel:[0,0,0] op_sel_hi:[0,1,1]
	v_pk_fma_f32 v[216:217], v[26:27], v[130:131], v[216:217] op_sel:[0,0,0] op_sel_hi:[0,1,1]
	s_waitcnt lgkmcnt(6)
	v_pk_fma_f32 v[218:219], v[26:27], v[132:133], v[218:219] op_sel:[0,0,0] op_sel_hi:[0,1,1]
	v_pk_fma_f32 v[220:221], v[26:27], v[134:135], v[220:221] op_sel:[0,0,0] op_sel_hi:[0,1,1]
	s_waitcnt lgkmcnt(5)
	v_pk_fma_f32 v[222:223], v[26:27], v[136:137], v[222:223] op_sel:[0,0,0] op_sel_hi:[0,1,1]
	v_pk_fma_f32 v[224:225], v[26:27], v[138:139], v[224:225] op_sel:[0,0,0] op_sel_hi:[0,1,1]
	s_waitcnt lgkmcnt(4)
	v_pk_fma_f32 v[226:227], v[26:27], v[140:141], v[226:227] op_sel:[0,0,0] op_sel_hi:[0,1,1]
	v_pk_fma_f32 v[228:229], v[26:27], v[142:143], v[228:229] op_sel:[0,0,0] op_sel_hi:[0,1,1]
	s_waitcnt lgkmcnt(3)
	v_pk_fma_f32 v[214:215], v[26:27], v[144:145], v[214:215] op_sel:[1,0,0] op_sel_hi:[1,1,1]
	v_pk_fma_f32 v[216:217], v[26:27], v[146:147], v[216:217] op_sel:[1,0,0] op_sel_hi:[1,1,1]
	s_waitcnt lgkmcnt(2)
	v_pk_fma_f32 v[218:219], v[26:27], v[148:149], v[218:219] op_sel:[1,0,0] op_sel_hi:[1,1,1]
	v_pk_fma_f32 v[220:221], v[26:27], v[150:151], v[220:221] op_sel:[1,0,0] op_sel_hi:[1,1,1]
	s_waitcnt lgkmcnt(1)
	v_pk_fma_f32 v[222:223], v[26:27], v[152:153], v[222:223] op_sel:[1,0,0] op_sel_hi:[1,1,1]
	v_pk_fma_f32 v[224:225], v[26:27], v[154:155], v[224:225] op_sel:[1,0,0] op_sel_hi:[1,1,1]
	s_waitcnt lgkmcnt(0)
	v_pk_fma_f32 v[226:227], v[26:27], v[156:157], v[226:227] op_sel:[1,0,0] op_sel_hi:[1,1,1]
	v_pk_fma_f32 v[228:229], v[26:27], v[158:159], v[228:229] op_sel:[1,0,0] op_sel_hi:[1,1,1]
	s_mov_b32 s34, 0xaaaaaaaa
	s_mov_b32 s35, 0xaaaaaaaa
	s_mov_b32 s72, 0xcccccccc
	s_mov_b32 s73, 0xcccccccc
	v_permlane32_swap_b32_e32 v214, v222
	v_permlane32_swap_b32_e32 v215, v223
	v_permlane32_swap_b32_e32 v216, v224
	v_permlane32_swap_b32_e32 v217, v225
	v_permlane32_swap_b32_e32 v218, v226
	v_permlane32_swap_b32_e32 v219, v227
	v_permlane32_swap_b32_e32 v220, v228
	v_permlane32_swap_b32_e32 v221, v229
	v_add_f32_e32 v214, v214, v222
	v_add_f32_e32 v215, v215, v223
	v_add_f32_e32 v216, v216, v224
	v_add_f32_e32 v217, v217, v225
	v_add_f32_e32 v218, v218, v226
	v_add_f32_e32 v219, v219, v227
	v_add_f32_e32 v220, v220, v228
	v_add_f32_e32 v221, v221, v229
	v_permlane16_swap_b32_e32 v214, v218
	v_permlane16_swap_b32_e32 v215, v219
	v_permlane16_swap_b32_e32 v216, v220
	v_permlane16_swap_b32_e32 v217, v221
	v_add_f32_e32 v214, v214, v218
	v_add_f32_e32 v215, v215, v219
	v_add_f32_e32 v216, v216, v220
	v_add_f32_e32 v217, v217, v221
	v_add_f32_dpp v230, v214, v214 quad_perm:[1,0,3,2] row_mask:0xf bank_mask:0xf
	v_add_f32_dpp v231, v215, v215 quad_perm:[1,0,3,2] row_mask:0xf bank_mask:0xf
	v_add_f32_dpp v232, v216, v216 quad_perm:[1,0,3,2] row_mask:0xf bank_mask:0xf
	v_add_f32_dpp v233, v217, v217 quad_perm:[1,0,3,2] row_mask:0xf bank_mask:0xf
	v_cndmask_b32_e64 v234, v230, v231, s[34:35]
	v_cndmask_b32_e64 v235, v232, v233, s[34:35]
	s_nop 1
	v_add_f32_dpp v236, v234, v234 quad_perm:[2,3,0,1] row_mask:0xf bank_mask:0xf
	v_add_f32_dpp v237, v235, v235 quad_perm:[2,3,0,1] row_mask:0xf bank_mask:0xf
	v_and_b32_e32 v239, 3, v190
	v_lshlrev_b32_e32 v240, 2, v190
	v_cndmask_b32_e64 v238, v236, v237, s[72:73]
	v_and_b32_e32 v240, 0x30, v240
	v_or_b32_e32 v239, v239, v240
	v_add_f32_dpp v238, v238, v238 row_ror:4 row_mask:0xf bank_mask:0xf
	v_lshlrev_b32_e32 v239, 2, v239
	s_nop 1
	v_add_f32_dpp v238, v238, v238 row_ror:8 row_mask:0xf bank_mask:0xf
	s_nop 0
	ds_bpermute_b32 v1, v239, v238
	s_waitcnt lgkmcnt(0)
	s_and_saveexec_b64 s[12:13], vcc
	s_cbranch_execz .LBB0_78
	v_lshl_add_u64 v[26:27], s[94:95], 0, v[24:25]
	global_store_dword v[26:27], v1, off
	s_branch .LBB0_78
